# K-loop back-edge rotation (7.11): pointer/counter/exit-test SALU moved in front of the loop-back barrier
# baseline (speedup 1.0000x reference)
.Lprio_done:
	s_add_u32 s0, s90, 0x80
	s_addc_u32 s1, s91, 0
	s_add_u32 s11, s2, 0x100
	s_addc_u32 s24, s3, 0
	s_mov_b32 s2, 0
	s_add_i32 s90, s2, 2
	s_add_u32 s82, s0, 0x80
	s_addc_u32 s3, s1, 0
	s_add_i32 s83, 0, 0x10000
	s_cmp_eq_u32 s62, s2
	s_cselect_b32 s3, s23, s3
	s_cselect_b32 s2, s22, s82
	s_cselect_b32 vcc_hi, s13, s24
	s_cselect_b32 vcc_lo, s12, s11
	s_add_i32 s82, 0, 0x14000
	v_add_u32_e32 v140, s83, v157
	v_add_u32_e32 v144, s82, v157
	ds_read_b128 v[128:131], v140
	ds_read_b128 v[132:135], v140 offset:1024
	ds_read_b128 v[136:139], v140 offset:2048
	ds_read_b128 v[140:143], v140 offset:3072
	ds_read_b128 v[166:169], v144
	ds_read_b128 v[176:179], v144 offset:1024
	ds_read_b128 v[180:183], v144 offset:2048
	ds_read_b128 v[184:187], v144 offset:3072
	v_lshl_add_u64 v[170:171], s[0:1], 0, v[160:161]
	s_add_i32 m0, s37, 0xc000
	ds_read_b128 v[188:191], v242
	ds_read_b128 v[192:195], v242 offset:1024
	ds_read_b128 v[196:199], v242 offset:2048
	ds_read_b128 v[200:203], v242 offset:3072
	ds_read_b128 v[204:207], v242 offset:4096
	ds_read_b128 v[208:211], v242 offset:5120
	ds_read_b128 v[212:215], v242 offset:6144
	ds_read_b128 v[216:219], v242 offset:7168
	global_load_lds_dwordx4 v[170:171], off
	v_lshl_add_u64 v[170:171], s[0:1], 0, v[162:163]
	s_add_i32 m0, s37, 0xe000
	s_nop 0
	global_load_lds_dwordx4 v[170:171], off
	s_waitcnt vmcnt(8) lgkmcnt(0)
	s_barrier
	v_mfma_f32_16x16x32_bf16 v[124:127], v[128:131], v[188:191], 0
	v_mfma_f32_16x16x32_bf16 v[120:123], v[136:139], v[188:191], 0
	v_mfma_f32_16x16x32_bf16 v[108:111], v[128:131], v[196:199], 0
	v_mfma_f32_16x16x32_bf16 v[104:107], v[136:139], v[196:199], 0
	v_mfma_f32_16x16x32_bf16 v[92:95], v[128:131], v[204:207], 0
	v_mfma_f32_16x16x32_bf16 v[88:91], v[136:139], v[204:207], 0
	v_mfma_f32_16x16x32_bf16 v[76:79], v[128:131], v[212:215], 0
	v_mfma_f32_16x16x32_bf16 v[72:75], v[136:139], v[212:215], 0
	v_mfma_f32_16x16x32_bf16 v[124:127], v[132:135], v[192:195], v[124:127]
	v_mfma_f32_16x16x32_bf16 v[120:123], v[140:143], v[192:195], v[120:123]
	v_mfma_f32_16x16x32_bf16 v[108:111], v[132:135], v[200:203], v[108:111]
	v_mfma_f32_16x16x32_bf16 v[104:107], v[140:143], v[200:203], v[104:107]
	v_mfma_f32_16x16x32_bf16 v[92:95], v[132:135], v[208:211], v[92:95]
	v_mfma_f32_16x16x32_bf16 v[88:91], v[140:143], v[208:211], v[88:91]
	v_mfma_f32_16x16x32_bf16 v[76:79], v[132:135], v[216:219], v[76:79]
	v_mfma_f32_16x16x32_bf16 v[72:75], v[140:143], v[216:219], v[72:75]
	v_mfma_f32_16x16x32_bf16 v[116:119], v[166:169], v[188:191], 0
	v_mfma_f32_16x16x32_bf16 v[112:115], v[180:183], v[188:191], 0
	v_mfma_f32_16x16x32_bf16 v[100:103], v[166:169], v[196:199], 0
	v_mfma_f32_16x16x32_bf16 v[96:99], v[180:183], v[196:199], 0
	v_mfma_f32_16x16x32_bf16 v[84:87], v[166:169], v[204:207], 0
	v_mfma_f32_16x16x32_bf16 v[80:83], v[180:183], v[204:207], 0
	v_mfma_f32_16x16x32_bf16 v[68:71], v[166:169], v[212:215], 0
	v_mfma_f32_16x16x32_bf16 v[64:67], v[180:183], v[212:215], 0
	v_mfma_f32_16x16x32_bf16 v[116:119], v[176:179], v[192:195], v[116:119]
	v_mfma_f32_16x16x32_bf16 v[112:115], v[184:187], v[192:195], v[112:115]
	v_mfma_f32_16x16x32_bf16 v[100:103], v[176:179], v[200:203], v[100:103]
	v_mfma_f32_16x16x32_bf16 v[96:99], v[184:187], v[200:203], v[96:99]
	v_mfma_f32_16x16x32_bf16 v[84:87], v[176:179], v[208:211], v[84:87]
	v_mfma_f32_16x16x32_bf16 v[80:83], v[184:187], v[208:211], v[80:83]
	v_mfma_f32_16x16x32_bf16 v[68:71], v[176:179], v[216:219], v[68:71]
	v_mfma_f32_16x16x32_bf16 v[64:67], v[184:187], v[216:219], v[64:67]
	s_barrier
	s_add_i32 s83, s83, s36
	v_lshl_add_u64 v[170:171], vcc, 0, v[150:151]
	s_mov_b32 m0, s83
	ds_read_b128 v[188:191], v242 offset:16384
	ds_read_b128 v[192:195], v242 offset:17408
	ds_read_b128 v[196:199], v242 offset:18432
	ds_read_b128 v[200:203], v242 offset:19456
	ds_read_b128 v[204:207], v242 offset:20480
	ds_read_b128 v[208:211], v242 offset:21504
	ds_read_b128 v[212:215], v242 offset:22528
	ds_read_b128 v[216:219], v242 offset:23552
	global_load_lds_dwordx4 v[170:171], off
	s_add_i32 m0, s83, 0x2000
	v_lshl_add_u64 v[232:233], vcc, 0, v[154:155]
	s_add_u32 vcc_lo, vcc_lo, s26
	s_addc_u32 vcc_hi, vcc_hi, 0
	s_add_i32 s82, s82, s36
	global_load_lds_dwordx4 v[232:233], off
	v_lshl_add_u64 v[234:235], vcc, 0, v[150:151]
	s_mov_b32 m0, s82
	v_lshl_add_u64 v[246:247], vcc, 0, v[154:155]
	global_load_lds_dwordx4 v[234:235], off
	s_add_i32 m0, s82, 0x2000
	v_lshl_add_u64 v[248:249], s[2:3], 0, v[148:149]
	global_load_lds_dwordx4 v[246:247], off
	s_mov_b32 m0, s37
	v_lshl_add_u64 v[250:251], s[2:3], 0, v[152:153]
	global_load_lds_dwordx4 v[248:249], off
	s_mov_b32 m0, s42
	s_nop 0
	global_load_lds_dwordx4 v[250:251], off
	s_waitcnt vmcnt(8) lgkmcnt(0)
	s_barrier
	v_mfma_f32_16x16x32_bf16 v[60:63], v[128:131], v[188:191], 0
	v_mfma_f32_16x16x32_bf16 v[56:59], v[136:139], v[188:191], 0
	v_mfma_f32_16x16x32_bf16 v[44:47], v[128:131], v[196:199], 0
	v_mfma_f32_16x16x32_bf16 v[40:43], v[136:139], v[196:199], 0
	v_mfma_f32_16x16x32_bf16 v[28:31], v[128:131], v[204:207], 0
	v_mfma_f32_16x16x32_bf16 v[24:27], v[136:139], v[204:207], 0
	v_mfma_f32_16x16x32_bf16 v[12:15], v[128:131], v[212:215], 0
	v_mfma_f32_16x16x32_bf16 v[8:11], v[136:139], v[212:215], 0
	v_mfma_f32_16x16x32_bf16 v[60:63], v[132:135], v[192:195], v[60:63]
	v_mfma_f32_16x16x32_bf16 v[56:59], v[140:143], v[192:195], v[56:59]
	v_mfma_f32_16x16x32_bf16 v[44:47], v[132:135], v[200:203], v[44:47]
	v_mfma_f32_16x16x32_bf16 v[40:43], v[140:143], v[200:203], v[40:43]
	v_mfma_f32_16x16x32_bf16 v[28:31], v[132:135], v[208:211], v[28:31]
	v_mfma_f32_16x16x32_bf16 v[24:27], v[140:143], v[208:211], v[24:27]
	v_mfma_f32_16x16x32_bf16 v[12:15], v[132:135], v[216:219], v[12:15]
	v_mfma_f32_16x16x32_bf16 v[8:11], v[140:143], v[216:219], v[8:11]
	v_mfma_f32_16x16x32_bf16 v[52:55], v[166:169], v[188:191], 0
	v_mfma_f32_16x16x32_bf16 v[48:51], v[180:183], v[188:191], 0
	v_mfma_f32_16x16x32_bf16 v[36:39], v[166:169], v[196:199], 0
	v_mfma_f32_16x16x32_bf16 v[32:35], v[180:183], v[196:199], 0
	v_mfma_f32_16x16x32_bf16 v[20:23], v[166:169], v[204:207], 0
	v_mfma_f32_16x16x32_bf16 v[16:19], v[180:183], v[204:207], 0
	v_mfma_f32_16x16x32_bf16 v[4:7], v[166:169], v[212:215], 0
	v_mfma_f32_16x16x32_bf16 v[0:3], v[180:183], v[212:215], 0
	v_mfma_f32_16x16x32_bf16 v[52:55], v[176:179], v[192:195], v[52:55]
	v_mfma_f32_16x16x32_bf16 v[48:51], v[184:187], v[192:195], v[48:51]
	v_mfma_f32_16x16x32_bf16 v[36:39], v[176:179], v[200:203], v[36:39]
	v_mfma_f32_16x16x32_bf16 v[32:35], v[184:187], v[200:203], v[32:35]
	v_mfma_f32_16x16x32_bf16 v[20:23], v[176:179], v[208:211], v[20:23]
	v_mfma_f32_16x16x32_bf16 v[16:19], v[184:187], v[208:211], v[16:19]
	v_mfma_f32_16x16x32_bf16 v[4:7], v[176:179], v[216:219], v[4:7]
	v_mfma_f32_16x16x32_bf16 v[0:3], v[184:187], v[216:219], v[0:3]
	s_barrier
	s_add_i32 s82, 0, 0x18000
	s_add_i32 s83, 0, 0x1c000
	v_add_u32_e32 v140, s82, v157
	v_add_u32_e32 v144, s83, v157
	ds_read_b128 v[128:131], v140
	ds_read_b128 v[132:135], v140 offset:1024
	ds_read_b128 v[136:139], v140 offset:2048
	ds_read_b128 v[140:143], v140 offset:3072
	ds_read_b128 v[166:169], v144
	ds_read_b128 v[176:179], v144 offset:1024
	ds_read_b128 v[180:183], v144 offset:2048
	ds_read_b128 v[184:187], v144 offset:3072
	s_add_u32 s2, s2, s58
	s_addc_u32 s3, s3, 0
	s_mov_b32 m0, s43
	v_lshl_add_u64 v[238:239], s[2:3], 0, v[148:149]
	ds_read_b128 v[188:191], v242 offset:32768
	ds_read_b128 v[192:195], v242 offset:33792
	ds_read_b128 v[196:199], v242 offset:34816
	ds_read_b128 v[200:203], v242 offset:35840
	ds_read_b128 v[204:207], v242 offset:36864
	ds_read_b128 v[208:211], v242 offset:37888
	ds_read_b128 v[212:215], v242 offset:38912
	ds_read_b128 v[216:219], v242 offset:39936
	global_load_lds_dwordx4 v[238:239], off
	v_lshl_add_u64 v[238:239], s[2:3], 0, v[152:153]
	s_mov_b32 m0, s16
	s_nop 0
	global_load_lds_dwordx4 v[238:239], off
	s_waitcnt vmcnt(8) lgkmcnt(0)
	s_barrier
	v_mfma_f32_16x16x32_bf16 v[124:127], v[128:131], v[188:191], v[124:127]
	v_mfma_f32_16x16x32_bf16 v[120:123], v[136:139], v[188:191], v[120:123]
	v_mfma_f32_16x16x32_bf16 v[108:111], v[128:131], v[196:199], v[108:111]
	v_mfma_f32_16x16x32_bf16 v[104:107], v[136:139], v[196:199], v[104:107]
	v_mfma_f32_16x16x32_bf16 v[92:95], v[128:131], v[204:207], v[92:95]
	v_mfma_f32_16x16x32_bf16 v[88:91], v[136:139], v[204:207], v[88:91]
	v_mfma_f32_16x16x32_bf16 v[76:79], v[128:131], v[212:215], v[76:79]
	v_mfma_f32_16x16x32_bf16 v[72:75], v[136:139], v[212:215], v[72:75]
	v_mfma_f32_16x16x32_bf16 v[124:127], v[132:135], v[192:195], v[124:127]
	v_mfma_f32_16x16x32_bf16 v[120:123], v[140:143], v[192:195], v[120:123]
	v_mfma_f32_16x16x32_bf16 v[108:111], v[132:135], v[200:203], v[108:111]
	v_mfma_f32_16x16x32_bf16 v[104:107], v[140:143], v[200:203], v[104:107]
	v_mfma_f32_16x16x32_bf16 v[92:95], v[132:135], v[208:211], v[92:95]
	v_mfma_f32_16x16x32_bf16 v[88:91], v[140:143], v[208:211], v[88:91]
	v_mfma_f32_16x16x32_bf16 v[76:79], v[132:135], v[216:219], v[76:79]
	v_mfma_f32_16x16x32_bf16 v[72:75], v[140:143], v[216:219], v[72:75]
	v_mfma_f32_16x16x32_bf16 v[116:119], v[166:169], v[188:191], v[116:119]
	v_mfma_f32_16x16x32_bf16 v[112:115], v[180:183], v[188:191], v[112:115]
	v_mfma_f32_16x16x32_bf16 v[100:103], v[166:169], v[196:199], v[100:103]
	v_mfma_f32_16x16x32_bf16 v[96:99], v[180:183], v[196:199], v[96:99]
	v_mfma_f32_16x16x32_bf16 v[84:87], v[166:169], v[204:207], v[84:87]
	v_mfma_f32_16x16x32_bf16 v[80:83], v[180:183], v[204:207], v[80:83]
	v_mfma_f32_16x16x32_bf16 v[68:71], v[166:169], v[212:215], v[68:71]
	v_mfma_f32_16x16x32_bf16 v[64:67], v[180:183], v[212:215], v[64:67]
	v_mfma_f32_16x16x32_bf16 v[116:119], v[176:179], v[192:195], v[116:119]
	v_mfma_f32_16x16x32_bf16 v[112:115], v[184:187], v[192:195], v[112:115]
	v_mfma_f32_16x16x32_bf16 v[100:103], v[176:179], v[200:203], v[100:103]
	v_mfma_f32_16x16x32_bf16 v[96:99], v[184:187], v[200:203], v[96:99]
	v_mfma_f32_16x16x32_bf16 v[84:87], v[176:179], v[208:211], v[84:87]
	v_mfma_f32_16x16x32_bf16 v[80:83], v[184:187], v[208:211], v[80:83]
	v_mfma_f32_16x16x32_bf16 v[68:71], v[176:179], v[216:219], v[68:71]
	v_mfma_f32_16x16x32_bf16 v[64:67], v[184:187], v[216:219], v[64:67]
	s_barrier
	s_add_i32 s2, s82, s36
	v_lshl_add_u64 v[170:171], v[170:171], 0, s[30:31]
	s_mov_b32 m0, s2
	ds_read_b128 v[188:191], v242 offset:49152
	ds_read_b128 v[192:195], v242 offset:50176
	ds_read_b128 v[196:199], v242 offset:51200
	ds_read_b128 v[200:203], v242 offset:52224
	ds_read_b128 v[204:207], v242 offset:53248
	ds_read_b128 v[208:211], v242 offset:54272
	ds_read_b128 v[212:215], v242 offset:55296
	ds_read_b128 v[216:219], v242 offset:56320
	global_load_lds_dwordx4 v[170:171], off
	v_lshl_add_u64 v[170:171], v[232:233], 0, s[30:31]
	s_add_i32 m0, s2, 0x2000
	s_add_i32 s2, s83, s36
	global_load_lds_dwordx4 v[170:171], off
	v_lshl_add_u64 v[170:171], v[234:235], 0, s[30:31]
	s_mov_b32 m0, s2
	s_nop 0
	global_load_lds_dwordx4 v[170:171], off
	v_lshl_add_u64 v[170:171], v[246:247], 0, s[30:31]
	s_add_i32 m0, s2, 0x2000
	s_nop 0
	global_load_lds_dwordx4 v[170:171], off
	v_lshl_add_u64 v[170:171], v[248:249], 0, s[30:31]
	s_mov_b32 m0, s63
	s_nop 0
	global_load_lds_dwordx4 v[170:171], off
	v_lshl_add_u64 v[170:171], v[250:251], 0, s[30:31]
	s_mov_b32 m0, s18
	s_nop 0
	global_load_lds_dwordx4 v[170:171], off
	s_waitcnt vmcnt(8) lgkmcnt(0)
	s_barrier
	v_mfma_f32_16x16x32_bf16 v[60:63], v[128:131], v[188:191], v[60:63]
	v_mfma_f32_16x16x32_bf16 v[56:59], v[136:139], v[188:191], v[56:59]
	v_mfma_f32_16x16x32_bf16 v[44:47], v[128:131], v[196:199], v[44:47]
	v_mfma_f32_16x16x32_bf16 v[40:43], v[136:139], v[196:199], v[40:43]
	v_mfma_f32_16x16x32_bf16 v[28:31], v[128:131], v[204:207], v[28:31]
	v_mfma_f32_16x16x32_bf16 v[24:27], v[136:139], v[204:207], v[24:27]
	v_mfma_f32_16x16x32_bf16 v[12:15], v[128:131], v[212:215], v[12:15]
	v_mfma_f32_16x16x32_bf16 v[8:11], v[136:139], v[212:215], v[8:11]
	v_mfma_f32_16x16x32_bf16 v[60:63], v[132:135], v[192:195], v[60:63]
	v_mfma_f32_16x16x32_bf16 v[56:59], v[140:143], v[192:195], v[56:59]
	v_mfma_f32_16x16x32_bf16 v[44:47], v[132:135], v[200:203], v[44:47]
	v_mfma_f32_16x16x32_bf16 v[40:43], v[140:143], v[200:203], v[40:43]
	v_mfma_f32_16x16x32_bf16 v[28:31], v[132:135], v[208:211], v[28:31]
	v_mfma_f32_16x16x32_bf16 v[24:27], v[140:143], v[208:211], v[24:27]
	v_mfma_f32_16x16x32_bf16 v[12:15], v[132:135], v[216:219], v[12:15]
	v_mfma_f32_16x16x32_bf16 v[8:11], v[140:143], v[216:219], v[8:11]
	v_mfma_f32_16x16x32_bf16 v[52:55], v[166:169], v[188:191], v[52:55]
	v_mfma_f32_16x16x32_bf16 v[48:51], v[180:183], v[188:191], v[48:51]
	v_mfma_f32_16x16x32_bf16 v[36:39], v[166:169], v[196:199], v[36:39]
	v_mfma_f32_16x16x32_bf16 v[32:35], v[180:183], v[196:199], v[32:35]
	v_mfma_f32_16x16x32_bf16 v[20:23], v[166:169], v[204:207], v[20:23]
	v_mfma_f32_16x16x32_bf16 v[16:19], v[180:183], v[204:207], v[16:19]
	v_mfma_f32_16x16x32_bf16 v[4:7], v[166:169], v[212:215], v[4:7]
	v_mfma_f32_16x16x32_bf16 v[0:3], v[180:183], v[212:215], v[0:3]
	v_mfma_f32_16x16x32_bf16 v[52:55], v[176:179], v[192:195], v[52:55]
	v_mfma_f32_16x16x32_bf16 v[48:51], v[184:187], v[192:195], v[48:51]
	v_mfma_f32_16x16x32_bf16 v[36:39], v[176:179], v[200:203], v[36:39]
	v_mfma_f32_16x16x32_bf16 v[32:35], v[184:187], v[200:203], v[32:35]
	v_mfma_f32_16x16x32_bf16 v[20:23], v[176:179], v[208:211], v[20:23]
	v_mfma_f32_16x16x32_bf16 v[16:19], v[184:187], v[208:211], v[16:19]
	v_mfma_f32_16x16x32_bf16 v[4:7], v[176:179], v[216:219], v[4:7]
	v_mfma_f32_16x16x32_bf16 v[0:3], v[184:187], v[216:219], v[0:3]
	s_add_u32 s0, s0, 0x100
	s_addc_u32 s1, s1, 0
	s_add_u32 s11, s11, 0x100
	s_addc_u32 s24, s24, 0
	s_cmp_ge_u32 s90, s60
	s_mov_b32 s2, s90
	s_cbranch_scc1 .Lk_exit
	s_add_i32 s90, s2, 2
	s_add_u32 s82, s0, 0x80
	s_addc_u32 s3, s1, 0
	s_add_i32 s83, 0, 0x10000
	s_cmp_eq_u32 s62, s2
	s_cselect_b32 s3, s23, s3
	s_cselect_b32 s2, s22, s82
	s_cselect_b32 vcc_hi, s13, s24
	s_cselect_b32 vcc_lo, s12, s11
	s_add_i32 s82, 0, 0x14000
	s_barrier
.LBB0_295:
	v_add_u32_e32 v140, s83, v157
	v_add_u32_e32 v144, s82, v157
	ds_read_b128 v[128:131], v140
	ds_read_b128 v[132:135], v140 offset:1024
	ds_read_b128 v[136:139], v140 offset:2048
	ds_read_b128 v[140:143], v140 offset:3072
	ds_read_b128 v[166:169], v144
	ds_read_b128 v[176:179], v144 offset:1024
	ds_read_b128 v[180:183], v144 offset:2048
	ds_read_b128 v[184:187], v144 offset:3072
	v_lshl_add_u64 v[170:171], s[0:1], 0, v[160:161]
	s_add_i32 m0, s37, 0xc000
	ds_read_b128 v[188:191], v242
	ds_read_b128 v[192:195], v242 offset:1024
	ds_read_b128 v[196:199], v242 offset:2048
	ds_read_b128 v[200:203], v242 offset:3072
	ds_read_b128 v[204:207], v242 offset:4096
	ds_read_b128 v[208:211], v242 offset:5120
	ds_read_b128 v[212:215], v242 offset:6144
	ds_read_b128 v[216:219], v242 offset:7168
	global_load_lds_dwordx4 v[170:171], off
	v_lshl_add_u64 v[170:171], s[0:1], 0, v[162:163]
	s_add_i32 m0, s37, 0xe000
	s_nop 0
	global_load_lds_dwordx4 v[170:171], off
	s_waitcnt vmcnt(8) lgkmcnt(0)
	s_barrier
	v_mfma_f32_16x16x32_bf16 v[124:127], v[128:131], v[188:191], v[124:127]
	v_mfma_f32_16x16x32_bf16 v[120:123], v[136:139], v[188:191], v[120:123]
	v_mfma_f32_16x16x32_bf16 v[108:111], v[128:131], v[196:199], v[108:111]
	v_mfma_f32_16x16x32_bf16 v[104:107], v[136:139], v[196:199], v[104:107]
	v_mfma_f32_16x16x32_bf16 v[92:95], v[128:131], v[204:207], v[92:95]
	v_mfma_f32_16x16x32_bf16 v[88:91], v[136:139], v[204:207], v[88:91]
	v_mfma_f32_16x16x32_bf16 v[76:79], v[128:131], v[212:215], v[76:79]
	v_mfma_f32_16x16x32_bf16 v[72:75], v[136:139], v[212:215], v[72:75]
	v_mfma_f32_16x16x32_bf16 v[124:127], v[132:135], v[192:195], v[124:127]
	v_mfma_f32_16x16x32_bf16 v[120:123], v[140:143], v[192:195], v[120:123]
	v_mfma_f32_16x16x32_bf16 v[108:111], v[132:135], v[200:203], v[108:111]
	v_mfma_f32_16x16x32_bf16 v[104:107], v[140:143], v[200:203], v[104:107]
	v_mfma_f32_16x16x32_bf16 v[92:95], v[132:135], v[208:211], v[92:95]
	v_mfma_f32_16x16x32_bf16 v[88:91], v[140:143], v[208:211], v[88:91]
	v_mfma_f32_16x16x32_bf16 v[76:79], v[132:135], v[216:219], v[76:79]
	v_mfma_f32_16x16x32_bf16 v[72:75], v[140:143], v[216:219], v[72:75]
	v_mfma_f32_16x16x32_bf16 v[116:119], v[166:169], v[188:191], v[116:119]
	v_mfma_f32_16x16x32_bf16 v[112:115], v[180:183], v[188:191], v[112:115]
	v_mfma_f32_16x16x32_bf16 v[100:103], v[166:169], v[196:199], v[100:103]
	v_mfma_f32_16x16x32_bf16 v[96:99], v[180:183], v[196:199], v[96:99]
	v_mfma_f32_16x16x32_bf16 v[84:87], v[166:169], v[204:207], v[84:87]
	v_mfma_f32_16x16x32_bf16 v[80:83], v[180:183], v[204:207], v[80:83]
	v_mfma_f32_16x16x32_bf16 v[68:71], v[166:169], v[212:215], v[68:71]
	v_mfma_f32_16x16x32_bf16 v[64:67], v[180:183], v[212:215], v[64:67]
	v_mfma_f32_16x16x32_bf16 v[116:119], v[176:179], v[192:195], v[116:119]
	v_mfma_f32_16x16x32_bf16 v[112:115], v[184:187], v[192:195], v[112:115]
	v_mfma_f32_16x16x32_bf16 v[100:103], v[176:179], v[200:203], v[100:103]
	v_mfma_f32_16x16x32_bf16 v[96:99], v[184:187], v[200:203], v[96:99]
	v_mfma_f32_16x16x32_bf16 v[84:87], v[176:179], v[208:211], v[84:87]
	v_mfma_f32_16x16x32_bf16 v[80:83], v[184:187], v[208:211], v[80:83]
	v_mfma_f32_16x16x32_bf16 v[68:71], v[176:179], v[216:219], v[68:71]
	v_mfma_f32_16x16x32_bf16 v[64:67], v[184:187], v[216:219], v[64:67]
	s_barrier
	s_add_i32 s83, s83, s36
	v_lshl_add_u64 v[170:171], vcc, 0, v[150:151]
	s_mov_b32 m0, s83
	ds_read_b128 v[188:191], v242 offset:16384
	ds_read_b128 v[192:195], v242 offset:17408
	ds_read_b128 v[196:199], v242 offset:18432
	ds_read_b128 v[200:203], v242 offset:19456
	ds_read_b128 v[204:207], v242 offset:20480
	ds_read_b128 v[208:211], v242 offset:21504
	ds_read_b128 v[212:215], v242 offset:22528
	ds_read_b128 v[216:219], v242 offset:23552
	global_load_lds_dwordx4 v[170:171], off
	s_add_i32 m0, s83, 0x2000
	v_lshl_add_u64 v[232:233], vcc, 0, v[154:155]
	s_add_u32 vcc_lo, vcc_lo, s26
	s_addc_u32 vcc_hi, vcc_hi, 0
	s_add_i32 s82, s82, s36
	global_load_lds_dwordx4 v[232:233], off
	v_lshl_add_u64 v[234:235], vcc, 0, v[150:151]
	s_mov_b32 m0, s82
	v_lshl_add_u64 v[246:247], vcc, 0, v[154:155]
	global_load_lds_dwordx4 v[234:235], off
	s_add_i32 m0, s82, 0x2000
	v_lshl_add_u64 v[248:249], s[2:3], 0, v[148:149]
	global_load_lds_dwordx4 v[246:247], off
	s_mov_b32 m0, s37
	v_lshl_add_u64 v[250:251], s[2:3], 0, v[152:153]
	global_load_lds_dwordx4 v[248:249], off
	s_mov_b32 m0, s42
	s_nop 0
	global_load_lds_dwordx4 v[250:251], off
	s_waitcnt vmcnt(8) lgkmcnt(0)
	s_barrier
	v_mfma_f32_16x16x32_bf16 v[60:63], v[128:131], v[188:191], v[60:63]
	v_mfma_f32_16x16x32_bf16 v[56:59], v[136:139], v[188:191], v[56:59]
	v_mfma_f32_16x16x32_bf16 v[44:47], v[128:131], v[196:199], v[44:47]
	v_mfma_f32_16x16x32_bf16 v[40:43], v[136:139], v[196:199], v[40:43]
	v_mfma_f32_16x16x32_bf16 v[28:31], v[128:131], v[204:207], v[28:31]
	v_mfma_f32_16x16x32_bf16 v[24:27], v[136:139], v[204:207], v[24:27]
	v_mfma_f32_16x16x32_bf16 v[12:15], v[128:131], v[212:215], v[12:15]
	v_mfma_f32_16x16x32_bf16 v[8:11], v[136:139], v[212:215], v[8:11]
	v_mfma_f32_16x16x32_bf16 v[60:63], v[132:135], v[192:195], v[60:63]
	v_mfma_f32_16x16x32_bf16 v[56:59], v[140:143], v[192:195], v[56:59]
	v_mfma_f32_16x16x32_bf16 v[44:47], v[132:135], v[200:203], v[44:47]
	v_mfma_f32_16x16x32_bf16 v[40:43], v[140:143], v[200:203], v[40:43]
	v_mfma_f32_16x16x32_bf16 v[28:31], v[132:135], v[208:211], v[28:31]
	v_mfma_f32_16x16x32_bf16 v[24:27], v[140:143], v[208:211], v[24:27]
	v_mfma_f32_16x16x32_bf16 v[12:15], v[132:135], v[216:219], v[12:15]
	v_mfma_f32_16x16x32_bf16 v[8:11], v[140:143], v[216:219], v[8:11]
	v_mfma_f32_16x16x32_bf16 v[52:55], v[166:169], v[188:191], v[52:55]
	v_mfma_f32_16x16x32_bf16 v[48:51], v[180:183], v[188:191], v[48:51]
	v_mfma_f32_16x16x32_bf16 v[36:39], v[166:169], v[196:199], v[36:39]
	v_mfma_f32_16x16x32_bf16 v[32:35], v[180:183], v[196:199], v[32:35]
	v_mfma_f32_16x16x32_bf16 v[20:23], v[166:169], v[204:207], v[20:23]
	v_mfma_f32_16x16x32_bf16 v[16:19], v[180:183], v[204:207], v[16:19]
	v_mfma_f32_16x16x32_bf16 v[4:7], v[166:169], v[212:215], v[4:7]
	v_mfma_f32_16x16x32_bf16 v[0:3], v[180:183], v[212:215], v[0:3]
	v_mfma_f32_16x16x32_bf16 v[52:55], v[176:179], v[192:195], v[52:55]
	v_mfma_f32_16x16x32_bf16 v[48:51], v[184:187], v[192:195], v[48:51]
	v_mfma_f32_16x16x32_bf16 v[36:39], v[176:179], v[200:203], v[36:39]
	v_mfma_f32_16x16x32_bf16 v[32:35], v[184:187], v[200:203], v[32:35]
	v_mfma_f32_16x16x32_bf16 v[20:23], v[176:179], v[208:211], v[20:23]
	v_mfma_f32_16x16x32_bf16 v[16:19], v[184:187], v[208:211], v[16:19]
	v_mfma_f32_16x16x32_bf16 v[4:7], v[176:179], v[216:219], v[4:7]
	v_mfma_f32_16x16x32_bf16 v[0:3], v[184:187], v[216:219], v[0:3]
	s_barrier
	s_add_i32 s82, 0, 0x18000
	s_add_i32 s83, 0, 0x1c000
	v_add_u32_e32 v140, s82, v157
	v_add_u32_e32 v144, s83, v157
	ds_read_b128 v[128:131], v140
	ds_read_b128 v[132:135], v140 offset:1024
	ds_read_b128 v[136:139], v140 offset:2048
	ds_read_b128 v[140:143], v140 offset:3072
	ds_read_b128 v[166:169], v144
	ds_read_b128 v[176:179], v144 offset:1024
	ds_read_b128 v[180:183], v144 offset:2048
	ds_read_b128 v[184:187], v144 offset:3072
	s_add_u32 s2, s2, s58
	s_addc_u32 s3, s3, 0
	s_mov_b32 m0, s43
	v_lshl_add_u64 v[238:239], s[2:3], 0, v[148:149]
	ds_read_b128 v[188:191], v242 offset:32768
	ds_read_b128 v[192:195], v242 offset:33792
	ds_read_b128 v[196:199], v242 offset:34816
	ds_read_b128 v[200:203], v242 offset:35840
	ds_read_b128 v[204:207], v242 offset:36864
	ds_read_b128 v[208:211], v242 offset:37888
	ds_read_b128 v[212:215], v242 offset:38912
	ds_read_b128 v[216:219], v242 offset:39936
	global_load_lds_dwordx4 v[238:239], off
	v_lshl_add_u64 v[238:239], s[2:3], 0, v[152:153]
	s_mov_b32 m0, s16
	s_nop 0
	global_load_lds_dwordx4 v[238:239], off
	s_waitcnt vmcnt(8) lgkmcnt(0)
	s_barrier
	v_mfma_f32_16x16x32_bf16 v[124:127], v[128:131], v[188:191], v[124:127]
	v_mfma_f32_16x16x32_bf16 v[120:123], v[136:139], v[188:191], v[120:123]
	v_mfma_f32_16x16x32_bf16 v[108:111], v[128:131], v[196:199], v[108:111]
	v_mfma_f32_16x16x32_bf16 v[104:107], v[136:139], v[196:199], v[104:107]
	v_mfma_f32_16x16x32_bf16 v[92:95], v[128:131], v[204:207], v[92:95]
	v_mfma_f32_16x16x32_bf16 v[88:91], v[136:139], v[204:207], v[88:91]
	v_mfma_f32_16x16x32_bf16 v[76:79], v[128:131], v[212:215], v[76:79]
	v_mfma_f32_16x16x32_bf16 v[72:75], v[136:139], v[212:215], v[72:75]
	v_mfma_f32_16x16x32_bf16 v[124:127], v[132:135], v[192:195], v[124:127]
	v_mfma_f32_16x16x32_bf16 v[120:123], v[140:143], v[192:195], v[120:123]
	v_mfma_f32_16x16x32_bf16 v[108:111], v[132:135], v[200:203], v[108:111]
	v_mfma_f32_16x16x32_bf16 v[104:107], v[140:143], v[200:203], v[104:107]
	v_mfma_f32_16x16x32_bf16 v[92:95], v[132:135], v[208:211], v[92:95]
	v_mfma_f32_16x16x32_bf16 v[88:91], v[140:143], v[208:211], v[88:91]
	v_mfma_f32_16x16x32_bf16 v[76:79], v[132:135], v[216:219], v[76:79]
	v_mfma_f32_16x16x32_bf16 v[72:75], v[140:143], v[216:219], v[72:75]
	v_mfma_f32_16x16x32_bf16 v[116:119], v[166:169], v[188:191], v[116:119]
	v_mfma_f32_16x16x32_bf16 v[112:115], v[180:183], v[188:191], v[112:115]
	v_mfma_f32_16x16x32_bf16 v[100:103], v[166:169], v[196:199], v[100:103]
	v_mfma_f32_16x16x32_bf16 v[96:99], v[180:183], v[196:199], v[96:99]
	v_mfma_f32_16x16x32_bf16 v[84:87], v[166:169], v[204:207], v[84:87]
	v_mfma_f32_16x16x32_bf16 v[80:83], v[180:183], v[204:207], v[80:83]
	v_mfma_f32_16x16x32_bf16 v[68:71], v[166:169], v[212:215], v[68:71]
	v_mfma_f32_16x16x32_bf16 v[64:67], v[180:183], v[212:215], v[64:67]
	v_mfma_f32_16x16x32_bf16 v[116:119], v[176:179], v[192:195], v[116:119]
	v_mfma_f32_16x16x32_bf16 v[112:115], v[184:187], v[192:195], v[112:115]
	v_mfma_f32_16x16x32_bf16 v[100:103], v[176:179], v[200:203], v[100:103]
	v_mfma_f32_16x16x32_bf16 v[96:99], v[184:187], v[200:203], v[96:99]
	v_mfma_f32_16x16x32_bf16 v[84:87], v[176:179], v[208:211], v[84:87]
	v_mfma_f32_16x16x32_bf16 v[80:83], v[184:187], v[208:211], v[80:83]
	v_mfma_f32_16x16x32_bf16 v[68:71], v[176:179], v[216:219], v[68:71]
	v_mfma_f32_16x16x32_bf16 v[64:67], v[184:187], v[216:219], v[64:67]
	s_barrier
	s_add_i32 s2, s82, s36
	v_lshl_add_u64 v[170:171], v[170:171], 0, s[30:31]
	s_mov_b32 m0, s2
	ds_read_b128 v[188:191], v242 offset:49152
	ds_read_b128 v[192:195], v242 offset:50176
	ds_read_b128 v[196:199], v242 offset:51200
	ds_read_b128 v[200:203], v242 offset:52224
	ds_read_b128 v[204:207], v242 offset:53248
	ds_read_b128 v[208:211], v242 offset:54272
	ds_read_b128 v[212:215], v242 offset:55296
	ds_read_b128 v[216:219], v242 offset:56320
	global_load_lds_dwordx4 v[170:171], off
	v_lshl_add_u64 v[170:171], v[232:233], 0, s[30:31]
	s_add_i32 m0, s2, 0x2000
	s_add_i32 s2, s83, s36
	global_load_lds_dwordx4 v[170:171], off
	v_lshl_add_u64 v[170:171], v[234:235], 0, s[30:31]
	s_mov_b32 m0, s2
	s_nop 0
	global_load_lds_dwordx4 v[170:171], off
	v_lshl_add_u64 v[170:171], v[246:247], 0, s[30:31]
	s_add_i32 m0, s2, 0x2000
	s_nop 0
	global_load_lds_dwordx4 v[170:171], off
	v_lshl_add_u64 v[170:171], v[248:249], 0, s[30:31]
	s_mov_b32 m0, s63
	s_nop 0
	global_load_lds_dwordx4 v[170:171], off
	v_lshl_add_u64 v[170:171], v[250:251], 0, s[30:31]
	s_mov_b32 m0, s18
	s_nop 0
	global_load_lds_dwordx4 v[170:171], off
	s_waitcnt vmcnt(8) lgkmcnt(0)
	s_barrier
	v_mfma_f32_16x16x32_bf16 v[60:63], v[128:131], v[188:191], v[60:63]
	v_mfma_f32_16x16x32_bf16 v[56:59], v[136:139], v[188:191], v[56:59]
	v_mfma_f32_16x16x32_bf16 v[44:47], v[128:131], v[196:199], v[44:47]
	v_mfma_f32_16x16x32_bf16 v[40:43], v[136:139], v[196:199], v[40:43]
	v_mfma_f32_16x16x32_bf16 v[28:31], v[128:131], v[204:207], v[28:31]
	v_mfma_f32_16x16x32_bf16 v[24:27], v[136:139], v[204:207], v[24:27]
	v_mfma_f32_16x16x32_bf16 v[12:15], v[128:131], v[212:215], v[12:15]
	v_mfma_f32_16x16x32_bf16 v[8:11], v[136:139], v[212:215], v[8:11]
	v_mfma_f32_16x16x32_bf16 v[60:63], v[132:135], v[192:195], v[60:63]
	v_mfma_f32_16x16x32_bf16 v[56:59], v[140:143], v[192:195], v[56:59]
	v_mfma_f32_16x16x32_bf16 v[44:47], v[132:135], v[200:203], v[44:47]
	v_mfma_f32_16x16x32_bf16 v[40:43], v[140:143], v[200:203], v[40:43]
	v_mfma_f32_16x16x32_bf16 v[28:31], v[132:135], v[208:211], v[28:31]
	v_mfma_f32_16x16x32_bf16 v[24:27], v[140:143], v[208:211], v[24:27]
	v_mfma_f32_16x16x32_bf16 v[12:15], v[132:135], v[216:219], v[12:15]
	v_mfma_f32_16x16x32_bf16 v[8:11], v[140:143], v[216:219], v[8:11]
	v_mfma_f32_16x16x32_bf16 v[52:55], v[166:169], v[188:191], v[52:55]
	v_mfma_f32_16x16x32_bf16 v[48:51], v[180:183], v[188:191], v[48:51]
	v_mfma_f32_16x16x32_bf16 v[36:39], v[166:169], v[196:199], v[36:39]
	v_mfma_f32_16x16x32_bf16 v[32:35], v[180:183], v[196:199], v[32:35]
	v_mfma_f32_16x16x32_bf16 v[20:23], v[166:169], v[204:207], v[20:23]
	v_mfma_f32_16x16x32_bf16 v[16:19], v[180:183], v[204:207], v[16:19]
	v_mfma_f32_16x16x32_bf16 v[4:7], v[166:169], v[212:215], v[4:7]
	v_mfma_f32_16x16x32_bf16 v[0:3], v[180:183], v[212:215], v[0:3]
	v_mfma_f32_16x16x32_bf16 v[52:55], v[176:179], v[192:195], v[52:55]
	v_mfma_f32_16x16x32_bf16 v[48:51], v[184:187], v[192:195], v[48:51]
	v_mfma_f32_16x16x32_bf16 v[36:39], v[176:179], v[200:203], v[36:39]
	v_mfma_f32_16x16x32_bf16 v[32:35], v[184:187], v[200:203], v[32:35]
	v_mfma_f32_16x16x32_bf16 v[20:23], v[176:179], v[208:211], v[20:23]
	v_mfma_f32_16x16x32_bf16 v[16:19], v[184:187], v[208:211], v[16:19]
	v_mfma_f32_16x16x32_bf16 v[4:7], v[176:179], v[216:219], v[4:7]
	v_mfma_f32_16x16x32_bf16 v[0:3], v[184:187], v[216:219], v[0:3]
	s_add_u32 s0, s0, 0x100
	s_addc_u32 s1, s1, 0
	s_add_u32 s11, s11, 0x100
	s_addc_u32 s24, s24, 0
	s_cmp_ge_u32 s90, s60
	s_mov_b32 s2, s90
	s_cbranch_scc1 .Lk_exit
	s_add_i32 s90, s2, 2
	s_add_u32 s82, s0, 0x80
	s_addc_u32 s3, s1, 0
	s_add_i32 s83, 0, 0x10000
	s_cmp_eq_u32 s62, s2
	s_cselect_b32 s3, s23, s3
	s_cselect_b32 s2, s22, s82
	s_cselect_b32 vcc_hi, s13, s24
	s_cselect_b32 vcc_lo, s12, s11
	s_add_i32 s82, 0, 0x14000
	s_barrier
	s_branch .LBB0_295
.Lk_exit:
	s_barrier
	s_branch .LBB0_297
